# fast path softmax row-sum as a 4-level add tree instead of a 16-long dependent chain
# speedup vs baseline: 1.0059x; 1.0014x over previous
; __device__ __forceinline__ unsigned cvt_pk_bf16(float lo, float hi) { unsigned r; asm volatile("v_cvt_pk_bf16_f32 %0, %1, %2" : "=v"(r) : "v"(lo), "v"(hi)); return r; }
; __device__ __forceinline__ f32x4 mfma16(bf16x8 a, bf16x8 b, f32x4 c) { return __builtin_amdgcn_mfma_f32_16x16x32_bf16(a, b, c, 0, 0, 0); }
; template <int MODE> __device__ __forceinline__ void tile_softmax(f32x4 (&S)[4], bool rowv, int kfirst, int klo, unsigned kspan, float& l) {
;     ...
;         for (int j = 0; j < 4; ++j) { float e = __builtin_amdgcn_exp2f(S[st][j]);
;             if (MODE == 1) e = rowv ? e : 0.f;
;             if (MODE == 2) e = ((unsigned)(kfirst + st * 16 + j - klo) <= kspan) ? e : 0.f;
;             S[st][j] = e; ps += e; }
;     l += ps;
; __device__ __forceinline__ void nsa_pack(const f32x4 (&P)[4], u32x4 (&pf)[2]) {
; #pragma unroll
;     for (int hf = 0; hf < 2; ++hf) { pf[hf].x = cvt_pk_bf16(P[2 * hf][0], P[2 * hf][1]); pf[hf].y = cvt_pk_bf16(P[2 * hf][2], P[2 * hf][3]); pf[hf].z = cvt_pk_bf16(P[2 * hf + 1][0], P[2 * hf + 1][1]); pf[hf].w = cvt_pk_bf16(P[2 * hf + 1][2], P[2 * hf + 1][3]); }
; }
; __device__ __forceinline__ void nsa_pv(const u32x4 (&vf)[2][4], const u32x4 (&pf)[2], f32x4 (&O)[4]) {
; #pragma unroll
;     for (int hf = 0; hf < 2; ++hf)
; #pragma unroll
;         for (int dt = 0; dt < 4; ++dt) O[dt] = mfma16(__builtin_bit_cast(bf16x8, vf[hf][dt]), __builtin_bit_cast(bf16x8, pf[hf]), O[dt]);
; }
.Lsel_fast_k:
	v_add_u32_e32 v126, s45, v197
	v_add_u32_e32 v127, s45, v198
	v_add_u32_e32 v128, s45, v199
	v_add_u32_e32 v129, s45, v206
	s_waitcnt lgkmcnt(0)
	s_and_b64 vcc, exec, s[56:57]
	s_cbranch_vccz .Lsf_only1
	s_and_b64 vcc, exec, s[28:29]
	s_cbranch_vccz .Lsf_only0
	v_mfma_f32_16x16x32_bf16 v[16:19], v[132:135], v[60:63], 0
	v_mfma_f32_16x16x32_bf16 v[20:23], v[136:139], v[60:63], 0
	v_mfma_f32_16x16x32_bf16 v[24:27], v[140:143], v[60:63], 0
	v_mfma_f32_16x16x32_bf16 v[28:31], v[144:147], v[60:63], 0
	v_mfma_f32_16x16x32_bf16 v[16:19], v[148:151], v[72:75], v[16:19]
	v_mfma_f32_16x16x32_bf16 v[20:23], v[152:155], v[72:75], v[20:23]
	v_mfma_f32_16x16x32_bf16 v[24:27], v[116:119], v[72:75], v[24:27]
	v_mfma_f32_16x16x32_bf16 v[28:31], v[120:123], v[72:75], v[28:31]
	v_mfma_f32_16x16x32_bf16 v[32:35], v[132:135], v[76:79], 0
	v_mfma_f32_16x16x32_bf16 v[36:39], v[136:139], v[76:79], 0
	v_mfma_f32_16x16x32_bf16 v[40:43], v[140:143], v[76:79], 0
	v_mfma_f32_16x16x32_bf16 v[44:47], v[144:147], v[76:79], 0
	v_mfma_f32_16x16x32_bf16 v[32:35], v[148:151], v[80:83], v[32:35]
	v_mfma_f32_16x16x32_bf16 v[36:39], v[152:155], v[80:83], v[36:39]
	v_mfma_f32_16x16x32_bf16 v[40:43], v[116:119], v[80:83], v[40:43]
	v_mfma_f32_16x16x32_bf16 v[44:47], v[120:123], v[80:83], v[44:47]
	s_nop 3
	ds_read_b64 v[132:133], v126 offset:8192
	ds_read_b64 v[134:135], v127 offset:8192
	ds_read_b64 v[148:149], v128 offset:8192
	ds_read_b64 v[150:151], v129 offset:8192
	ds_read_b64 v[136:137], v126 offset:10240
	ds_read_b64 v[138:139], v127 offset:10240
	ds_read_b64 v[152:153], v128 offset:10240
	ds_read_b64 v[154:155], v129 offset:10240
	ds_read_b64 v[140:141], v126 offset:12288
	ds_read_b64 v[142:143], v127 offset:12288
	ds_read_b64 v[116:117], v128 offset:12288
	ds_read_b64 v[118:119], v129 offset:12288
	ds_read_b64 v[144:145], v126 offset:14336
	ds_read_b64 v[146:147], v127 offset:14336
	ds_read_b64 v[120:121], v128 offset:14336
	ds_read_b64 v[122:123], v129 offset:14336
	v_exp_f32_e32 v16, v16
	v_exp_f32_e32 v17, v17
	v_exp_f32_e32 v18, v18
	v_exp_f32_e32 v19, v19
	v_exp_f32_e32 v20, v20
	v_exp_f32_e32 v21, v21
	v_exp_f32_e32 v22, v22
	v_exp_f32_e32 v23, v23
	v_exp_f32_e32 v24, v24
	v_exp_f32_e32 v25, v25
	v_exp_f32_e32 v26, v26
	v_exp_f32_e32 v27, v27
	v_exp_f32_e32 v28, v28
	v_exp_f32_e32 v29, v29
	v_exp_f32_e32 v30, v30
	v_exp_f32_e32 v31, v31
	v_add_f32_e32 v124, v16, v17
	v_add_f32_e32 v125, v18, v19
	v_add_f32_e32 v126, v20, v21
	v_add_f32_e32 v127, v22, v23
	v_add_f32_e32 v128, v24, v25
	v_add_f32_e32 v129, v26, v27
	v_add_f32_e32 v251, v28, v29
	v_add_f32_e32 v252, v30, v31
	v_add_f32_e32 v124, v124, v125
	v_add_f32_e32 v125, v126, v127
	v_add_f32_e32 v126, v128, v129
	v_add_f32_e32 v127, v251, v252
	v_add_f32_e32 v124, v124, v125
	v_add_f32_e32 v125, v126, v127
	v_add_f32_e32 v124, v124, v125
	s_cmp_eq_u64 s[98:99], -1
	s_cbranch_scc1 .Lsf_b0_a
	v_cndmask_b32_e64 v253, 0, -1, s[98:99]
	v_and_b32_e32 v124, v124, v253
.Lsf_b0_a:
	v_add_f32_e32 v172, v172, v124
	v_cvt_pk_bf16_f32 v16, v16, v17
	v_cvt_pk_bf16_f32 v17, v18, v19
	v_cvt_pk_bf16_f32 v18, v20, v21
	v_cvt_pk_bf16_f32 v19, v22, v23
	v_cvt_pk_bf16_f32 v20, v24, v25
	v_cvt_pk_bf16_f32 v21, v26, v27
	v_cvt_pk_bf16_f32 v22, v28, v29
	v_cvt_pk_bf16_f32 v23, v30, v31
	s_cmp_eq_u64 s[98:99], -1
	s_cbranch_scc1 .Lsf_b0_b
	v_and_b32_e32 v16, v16, v253
	v_and_b32_e32 v17, v17, v253
	v_and_b32_e32 v18, v18, v253
	v_and_b32_e32 v19, v19, v253
	v_and_b32_e32 v20, v20, v253
	v_and_b32_e32 v21, v21, v253
	v_and_b32_e32 v22, v22, v253
	v_and_b32_e32 v23, v23, v253
.Lsf_b0_b:
	s_waitcnt lgkmcnt(0)
	s_nop 0
	v_exp_f32_e32 v32, v32
	v_exp_f32_e32 v33, v33
	v_mfma_f32_16x16x32_bf16 v[112:115], v[132:135], v[16:19], v[112:115]
	v_exp_f32_e32 v34, v34
	v_exp_f32_e32 v35, v35
	v_mfma_f32_16x16x32_bf16 v[108:111], v[136:139], v[16:19], v[108:111]
	v_exp_f32_e32 v36, v36
	v_exp_f32_e32 v37, v37
	v_mfma_f32_16x16x32_bf16 v[104:107], v[140:143], v[16:19], v[104:107]
	v_exp_f32_e32 v38, v38
	v_exp_f32_e32 v39, v39
	v_mfma_f32_16x16x32_bf16 v[100:103], v[144:147], v[16:19], v[100:103]
	v_exp_f32_e32 v40, v40
	v_exp_f32_e32 v41, v41
	v_mfma_f32_16x16x32_bf16 v[112:115], v[148:151], v[20:23], v[112:115]
	v_exp_f32_e32 v42, v42
	v_exp_f32_e32 v43, v43
	v_mfma_f32_16x16x32_bf16 v[108:111], v[152:155], v[20:23], v[108:111]
	v_exp_f32_e32 v44, v44
	v_exp_f32_e32 v45, v45
	v_mfma_f32_16x16x32_bf16 v[104:107], v[116:119], v[20:23], v[104:107]
	v_exp_f32_e32 v46, v46
	v_exp_f32_e32 v47, v47
	v_mfma_f32_16x16x32_bf16 v[100:103], v[120:123], v[20:23], v[100:103]
	v_add_f32_e32 v124, v32, v33
	v_add_f32_e32 v125, v34, v35
	v_add_f32_e32 v126, v36, v37
	v_add_f32_e32 v127, v38, v39
	v_add_f32_e32 v128, v40, v41
	v_add_f32_e32 v129, v42, v43
	v_add_f32_e32 v251, v44, v45
	v_add_f32_e32 v252, v46, v47
	v_add_f32_e32 v124, v124, v125
	v_add_f32_e32 v125, v126, v127
	v_add_f32_e32 v126, v128, v129
	v_add_f32_e32 v127, v251, v252
	v_add_f32_e32 v124, v124, v125
	v_add_f32_e32 v125, v126, v127
	v_add_f32_e32 v124, v124, v125
	s_cmp_eq_u64 s[100:101], -1
	s_cbranch_scc1 .Lsf_b1_a
	v_cndmask_b32_e64 v253, 0, -1, s[100:101]
	v_and_b32_e32 v124, v124, v253
.Lsf_b1_a:
	v_add_f32_e32 v173, v173, v124
	v_cvt_pk_bf16_f32 v32, v32, v33
	v_cvt_pk_bf16_f32 v33, v34, v35
	v_cvt_pk_bf16_f32 v34, v36, v37
	v_cvt_pk_bf16_f32 v35, v38, v39
	v_cvt_pk_bf16_f32 v36, v40, v41
	v_cvt_pk_bf16_f32 v37, v42, v43
	v_cvt_pk_bf16_f32 v38, v44, v45
	v_cvt_pk_bf16_f32 v39, v46, v47
	s_cmp_eq_u64 s[100:101], -1
	s_cbranch_scc1 .Lsf_b1_b
	v_and_b32_e32 v32, v32, v253
	v_and_b32_e32 v33, v33, v253
	v_and_b32_e32 v34, v34, v253
	v_and_b32_e32 v35, v35, v253
	v_and_b32_e32 v36, v36, v253
	v_and_b32_e32 v37, v37, v253
	v_and_b32_e32 v38, v38, v253
	v_and_b32_e32 v39, v39, v253

; template <int MODE> __device__ __forceinline__ void tile_softmax(f32x4 (&S)[4], bool rowv, int kfirst, int klo, unsigned kspan, float& l) {
;     ...
;         for (int j = 0; j < 4; ++j) { float e = __builtin_amdgcn_exp2f(S[st][j]);
;             if (MODE == 1) e = rowv ? e : 0.f;
;             if (MODE == 2) e = ((unsigned)(kfirst + st * 16 + j - klo) <= kspan) ? e : 0.f;
;             S[st][j] = e; ps += e; }
;     l += ps;
.Lsf_only0:
	v_mfma_f32_16x16x32_bf16 v[16:19], v[132:135], v[60:63], 0
	v_mfma_f32_16x16x32_bf16 v[20:23], v[136:139], v[60:63], 0
	v_mfma_f32_16x16x32_bf16 v[24:27], v[140:143], v[60:63], 0
	v_mfma_f32_16x16x32_bf16 v[28:31], v[144:147], v[60:63], 0
	v_mfma_f32_16x16x32_bf16 v[16:19], v[148:151], v[72:75], v[16:19]
	v_mfma_f32_16x16x32_bf16 v[20:23], v[152:155], v[72:75], v[20:23]
	v_mfma_f32_16x16x32_bf16 v[24:27], v[116:119], v[72:75], v[24:27]
	v_mfma_f32_16x16x32_bf16 v[28:31], v[120:123], v[72:75], v[28:31]
	s_nop 3
	ds_read_b64 v[132:133], v126 offset:8192
	ds_read_b64 v[134:135], v127 offset:8192
	ds_read_b64 v[148:149], v128 offset:8192
	ds_read_b64 v[150:151], v129 offset:8192
	ds_read_b64 v[136:137], v126 offset:10240
	ds_read_b64 v[138:139], v127 offset:10240
	ds_read_b64 v[152:153], v128 offset:10240
	ds_read_b64 v[154:155], v129 offset:10240
	ds_read_b64 v[140:141], v126 offset:12288
	ds_read_b64 v[142:143], v127 offset:12288
	ds_read_b64 v[116:117], v128 offset:12288
	ds_read_b64 v[118:119], v129 offset:12288
	ds_read_b64 v[144:145], v126 offset:14336
	ds_read_b64 v[146:147], v127 offset:14336
	ds_read_b64 v[120:121], v128 offset:14336
	ds_read_b64 v[122:123], v129 offset:14336
	s_nop 7
	v_exp_f32_e32 v16, v16
	v_exp_f32_e32 v17, v17
	v_exp_f32_e32 v18, v18
	v_exp_f32_e32 v19, v19
	v_exp_f32_e32 v20, v20
	v_exp_f32_e32 v21, v21
	v_exp_f32_e32 v22, v22
	v_exp_f32_e32 v23, v23
	v_exp_f32_e32 v24, v24
	v_exp_f32_e32 v25, v25
	v_exp_f32_e32 v26, v26
	v_exp_f32_e32 v27, v27
	v_exp_f32_e32 v28, v28
	v_exp_f32_e32 v29, v29
	v_exp_f32_e32 v30, v30
	v_exp_f32_e32 v31, v31
	v_add_f32_e32 v124, v16, v17
	v_add_f32_e32 v125, v18, v19
	v_add_f32_e32 v126, v20, v21
	v_add_f32_e32 v127, v22, v23
	v_add_f32_e32 v128, v24, v25
	v_add_f32_e32 v129, v26, v27
	v_add_f32_e32 v251, v28, v29
	v_add_f32_e32 v252, v30, v31
	v_add_f32_e32 v124, v124, v125
	v_add_f32_e32 v125, v126, v127
	v_add_f32_e32 v126, v128, v129
	v_add_f32_e32 v127, v251, v252
	v_add_f32_e32 v124, v124, v125
	v_add_f32_e32 v125, v126, v127
	v_add_f32_e32 v124, v124, v125
	s_cmp_eq_u64 s[98:99], -1
	s_cbranch_scc1 .Lsf_o0_a
	v_cndmask_b32_e64 v253, 0, -1, s[98:99]
	v_and_b32_e32 v124, v124, v253

; template <int MODE> __device__ __forceinline__ void tile_softmax(f32x4 (&S)[4], bool rowv, int kfirst, int klo, unsigned kspan, float& l) {
;     ...
;         for (int j = 0; j < 4; ++j) { float e = __builtin_amdgcn_exp2f(S[st][j]);
;             if (MODE == 1) e = rowv ? e : 0.f;
;             if (MODE == 2) e = ((unsigned)(kfirst + st * 16 + j - klo) <= kspan) ? e : 0.f;
;             S[st][j] = e; ps += e; }
;     l += ps;
.Lsf_only1:
	v_mfma_f32_16x16x32_bf16 v[32:35], v[132:135], v[76:79], 0
	v_mfma_f32_16x16x32_bf16 v[36:39], v[136:139], v[76:79], 0
	v_mfma_f32_16x16x32_bf16 v[40:43], v[140:143], v[76:79], 0
	v_mfma_f32_16x16x32_bf16 v[44:47], v[144:147], v[76:79], 0
	v_mfma_f32_16x16x32_bf16 v[32:35], v[148:151], v[80:83], v[32:35]
	v_mfma_f32_16x16x32_bf16 v[36:39], v[152:155], v[80:83], v[36:39]
	v_mfma_f32_16x16x32_bf16 v[40:43], v[116:119], v[80:83], v[40:43]
	v_mfma_f32_16x16x32_bf16 v[44:47], v[120:123], v[80:83], v[44:47]
	s_nop 3
	ds_read_b64 v[132:133], v126 offset:8192
	ds_read_b64 v[134:135], v127 offset:8192
	ds_read_b64 v[148:149], v128 offset:8192
	ds_read_b64 v[150:151], v129 offset:8192
	ds_read_b64 v[136:137], v126 offset:10240
	ds_read_b64 v[138:139], v127 offset:10240
	ds_read_b64 v[152:153], v128 offset:10240
	ds_read_b64 v[154:155], v129 offset:10240
	ds_read_b64 v[140:141], v126 offset:12288
	ds_read_b64 v[142:143], v127 offset:12288
	ds_read_b64 v[116:117], v128 offset:12288
	ds_read_b64 v[118:119], v129 offset:12288
	ds_read_b64 v[144:145], v126 offset:14336
	ds_read_b64 v[146:147], v127 offset:14336
	ds_read_b64 v[120:121], v128 offset:14336
	ds_read_b64 v[122:123], v129 offset:14336
	s_nop 7
	v_exp_f32_e32 v32, v32
	v_exp_f32_e32 v33, v33
	v_exp_f32_e32 v34, v34
	v_exp_f32_e32 v35, v35
	v_exp_f32_e32 v36, v36
	v_exp_f32_e32 v37, v37
	v_exp_f32_e32 v38, v38
	v_exp_f32_e32 v39, v39
	v_exp_f32_e32 v40, v40
	v_exp_f32_e32 v41, v41
	v_exp_f32_e32 v42, v42
	v_exp_f32_e32 v43, v43
	v_exp_f32_e32 v44, v44
	v_exp_f32_e32 v45, v45
	v_exp_f32_e32 v46, v46
	v_exp_f32_e32 v47, v47
	v_add_f32_e32 v124, v32, v33
	v_add_f32_e32 v125, v34, v35
	v_add_f32_e32 v126, v36, v37
	v_add_f32_e32 v127, v38, v39
	v_add_f32_e32 v128, v40, v41
	v_add_f32_e32 v129, v42, v43
	v_add_f32_e32 v251, v44, v45
	v_add_f32_e32 v252, v46, v47
	v_add_f32_e32 v124, v124, v125
	v_add_f32_e32 v125, v126, v127
	v_add_f32_e32 v126, v128, v129
	v_add_f32_e32 v127, v251, v252
	v_add_f32_e32 v124, v124, v125
	v_add_f32_e32 v125, v126, v127
	v_add_f32_e32 v124, v124, v125
	s_cmp_eq_u64 s[100:101], -1
	s_cbranch_scc1 .Lsf_o1_a
	v_cndmask_b32_e64 v253, 0, -1, s[100:101]
	v_and_b32_e32 v124, v124, v253
